# deferred weight conversion: 17408 layer-2/3 weight tiles moved out of prep into the dilated-attention workgroups' slack in layers 0 and 2 (same hand-written conversion block, pointers stashed in v255
# baseline (speedup 1.0000x reference)
; __device__ __forceinline__ void conv_dispatch(const Params& P, int tile, int lane) {
;     const int j = tile / T_PAIR; int rem = tile % T_PAIR; unsigned char* ws = P.ws;
;     if (rem < T_EVEN) { const int i = 2 * j;
;         if (rem < T_WIN) { conv_tile(P.in[2] + (size_t)j * 2048 * 4096, (bf16_t*)(ws + WS_WIN + j * SZ_WIN), 2048, 4096, rem, lane, P.in[16] + (size_t)i * DM); return; } rem -= T_WIN;
;         if (rem < T_WOUT) { conv_tile(P.in[3] + (size_t)j * 2048 * 2048, (bf16_t*)(ws + WS_WOUT + j * SZ_WOUT), 2048, 2048, rem, lane, nullptr); return; } rem -= T_WOUT;
;         if (rem < T_GLU) { conv_tile(P.in[12] + (size_t)j * 1024 * 1024, (bf16_t*)(ws + WS_GLU + j * SZ_GLU), 1024, 1024, rem, lane, nullptr); return; } rem -= T_GLU;
;         if (rem < T_W1) { conv_tile(P.in[18] + (size_t)i * 2048 * 8192, (bf16_t*)(ws + WS_W1 + i * SZ_W1), 2048, 8192, rem, lane, P.in[17] + (size_t)i * DM); return; } rem -= T_W1;
;         conv_tile(P.in[19] + (size_t)i * 8192 * 2048, (bf16_t*)(ws + WS_W2 + i * SZ_W2), 8192, 2048, rem, lane, nullptr);
;     } else { rem -= T_EVEN; const int i = 2 * j + 1;
;         if (rem < T_QKV) { conv_tile(P.in[13] + (size_t)j * 2048 * 6144, (bf16_t*)(ws + WS_QKV + j * SZ_QKV), 2048, 6144, rem, lane, P.in[16] + (size_t)i * DM); return; } rem -= T_QKV;
;         if (rem < T_WOUT) { conv_tile(P.in[14] + (size_t)j * 2048 * 2048, (bf16_t*)(ws + WS_COUT + j * SZ_WOUT), 2048, 2048, rem, lane, nullptr); return; } rem -= T_WOUT;
;         if (rem < T_W1) { conv_tile(P.in[18] + (size_t)i * 2048 * 8192, (bf16_t*)(ws + WS_W1 + i * SZ_W1), 2048, 8192, rem, lane, P.in[17] + (size_t)i * DM); return; } rem -= T_W1;
;         conv_tile(P.in[19] + (size_t)i * 8192 * 2048, (bf16_t*)(ws + WS_W2 + i * SZ_W2), 8192, 2048, rem, lane, nullptr);
;     }
; }
; __global__ void __launch_bounds__(NTHR) hybrid_encoder_fwd(Params P) {
;     ...
;             constexpr int PB_PAIR = (T_PAIR - T_W1 - T_W2) / 4, NBATCH = 2 * PB_PAIR, NB1 = 11712;
;     ...
;             if (bid >= 128) for (int bt = (bid - 128) * 8 + wid; bt < NB1; bt += (G - 128) * 8) {
; #pragma unroll 1
;                 for (int q = 0; q < 4; ++q) conv_dispatch(P, PREP_TILE(bt) + q, lane); }
;             for (int bt = NB1 + bid * 8 + wid; bt < NBATCH; bt += G * 8) {
; #pragma unroll 1
;                 for (int q = 0; q < 4; ++q) conv_dispatch(P, PREP_TILE(bt) + q, lane); }
.LBB0_10:
	s_cmpk_gt_i32 s2, 0x7f
	s_cselect_b64 s[4:5], -1, 0
	v_writelane_b32 v253, s4, 14
	s_and_b64 vcc, exec, s[4:5]
	s_mov_b64 s[0:1], -1
	v_writelane_b32 v253, s5, 15
	s_mov_b32 s4, s22
	v_writelane_b32 v253, s4, 16
	s_nop 1
	v_writelane_b32 v253, s5, 17
	s_cbranch_vccz .LBB0_55
	s_add_i32 s3, s22, 0xfffffc00
	s_mov_b32 s25, 60
	s_mov_b32 s39, 13
	s_mov_b32 vcc_lo, 0x400
	s_mov_b32 vcc_hi, -1
.Lcv_entry:
	s_waitcnt lgkmcnt(0)
	v_writelane_b32 v255, s86, 0
	v_writelane_b32 v255, s87, 1
	v_writelane_b32 v255, s88, 2
	v_writelane_b32 v255, s89, 3
	v_writelane_b32 v255, s12, 4
	v_writelane_b32 v255, s13, 5
	v_writelane_b32 v255, s14, 6
	v_writelane_b32 v255, s15, 7
	v_writelane_b32 v255, s16, 8
	v_writelane_b32 v255, s17, 9
	v_writelane_b32 v255, s18, 10
	v_writelane_b32 v255, s19, 11
	v_and_b32_e32 v2, 7, v201
	v_lshrrev_b32_e32 v3, 3, v201
	v_lshlrev_b32_e32 v4, 4, v2
	v_lshlrev_b32_e32 v5, 4, v3
	v_lshlrev_b32_e32 v7, 5, v2
	s_mov_b32 s30, 0
	s_min_u32 s0, s30, s25
	s_mul_i32 s0, s0, vcc_lo
	s_add_i32 s0, s0, s3
	s_min_u32 s0, s0, vcc_hi
	s_add_i32 s30, s30, 1
	s_cmp_ge_u32 s0, 0x7a00
	s_cselect_b32 s33, 1, 0
	s_mul_i32 s1, s33, 0x7a00
	s_sub_i32 s20, s0, s1
	s_cmp_lt_u32 s20, 0x1000
	s_cbranch_scc1 .Lcv0_win
	s_cmp_lt_u32 s20, 0x1800
	s_cbranch_scc1 .Lcv0_wout
	s_cmp_lt_u32 s20, 0x1a00
	s_cbranch_scc1 .Lcv0_glu
	s_cmp_lt_u32 s20, 0x3a00
	s_cbranch_scc1 .Lcv0_w1
	s_cmp_lt_u32 s20, 0x5a00
	s_cbranch_scc1 .Lcv0_w2
	s_cmp_lt_u32 s20, 0x7200
	s_cbranch_scc1 .Lcv0_qkv

; __device__ __forceinline__ void conv_tile(const float* src, bf16_t* dst, int K, int N, int tile, int lane, const float* gk) {
;     const int tn = N >> 5; const int k0 = (tile / tn) * 64, n0 = (tile % tn) * 32; const int kg = lane & 7, jn = lane >> 3;
;     f32x4 v[8]; const float* sp = src + (size_t)(k0 + 8 * kg) * N + n0 + 4 * jn;
; #pragma unroll
;     for (int r = 0; r < 8; ++r) v[r] = *(const f32x4*)(sp + (size_t)r * N);
;     if (gk) { const f32x4 g0 = *(const f32x4*)(gk + k0 + 8 * kg), g1 = *(const f32x4*)(gk + k0 + 8 * kg + 4);
; #pragma unroll
;         for (int r = 0; r < 4; ++r) { v[r] *= g0[r]; v[4 + r] *= g1[r]; } }
; #pragma unroll
;     for (int i = 0; i < 4; ++i) { u32x4 w; w.x = cvt_pk_bf16(v[0][i], v[1][i]); w.y = cvt_pk_bf16(v[2][i], v[3][i]); w.z = cvt_pk_bf16(v[4][i], v[5][i]); w.w = cvt_pk_bf16(v[6][i], v[7][i]);
;         *(u32x4*)(dst + (size_t)(n0 + 4 * jn + i) * K + k0 + 8 * kg) = w; }
; }
; __device__ __forceinline__ void conv_dispatch(const Params& P, int tile, int lane) {
;     const int j = tile / T_PAIR; int rem = tile % T_PAIR; unsigned char* ws = P.ws;
;     if (rem < T_EVEN) { const int i = 2 * j;
;         if (rem < T_WIN) { conv_tile(P.in[2] + (size_t)j * 2048 * 4096, (bf16_t*)(ws + WS_WIN + j * SZ_WIN), 2048, 4096, rem, lane, P.in[16] + (size_t)i * DM); return; } rem -= T_WIN;
;         if (rem < T_WOUT) { conv_tile(P.in[3] + (size_t)j * 2048 * 2048, (bf16_t*)(ws + WS_WOUT + j * SZ_WOUT), 2048, 2048, rem, lane, nullptr); return; } rem -= T_WOUT;
;         if (rem < T_GLU) { conv_tile(P.in[12] + (size_t)j * 1024 * 1024, (bf16_t*)(ws + WS_GLU + j * SZ_GLU), 1024, 1024, rem, lane, nullptr); return; } rem -= T_GLU;
;         if (rem < T_W1) { conv_tile(P.in[18] + (size_t)i * 2048 * 8192, (bf16_t*)(ws + WS_W1 + i * SZ_W1), 2048, 8192, rem, lane, P.in[17] + (size_t)i * DM); return; } rem -= T_W1;
;         conv_tile(P.in[19] + (size_t)i * 8192 * 2048, (bf16_t*)(ws + WS_W2 + i * SZ_W2), 8192, 2048, rem, lane, nullptr);
;     } else { rem -= T_EVEN; const int i = 2 * j + 1;
;         if (rem < T_QKV) { conv_tile(P.in[13] + (size_t)j * 2048 * 6144, (bf16_t*)(ws + WS_QKV + j * SZ_QKV), 2048, 6144, rem, lane, P.in[16] + (size_t)i * DM); return; } rem -= T_QKV;
;         if (rem < T_WOUT) { conv_tile(P.in[14] + (size_t)j * 2048 * 2048, (bf16_t*)(ws + WS_COUT + j * SZ_WOUT), 2048, 2048, rem, lane, nullptr); return; } rem -= T_WOUT;
.Lcv0_dd:
	s_lshl_b32 s1, s10, 6
	s_mul_i32 s1, s1, s22
	s_lshl_b32 s24, s23, 7
	s_add_u32 s1, s1, s24
	s_add_u32 s4, s4, s1
	s_addc_u32 s5, s5, 0
	s_lshl_b32 s1, s11, 5
	s_mul_i32 s1, s1, s23
	s_lshl_b32 s24, s22, 7
	s_add_u32 s1, s1, s24
	s_add_u32 s72, s6, s1
	s_addc_u32 s73, s7, 0
	s_mov_b32 s74, s11
	s_lshl_b32 s1, s22, 8
	s_cmp_eq_u32 s75, 0
	s_cselect_b32 s8, s4, s8
	s_cselect_b32 s9, s5, s9
	s_cselect_b32 s1, 0, s1
	s_add_u32 s8, s8, s1
	s_addc_u32 s9, s9, 0
	s_lshl_b32 s1, s10, 3
	v_mul_lo_u32 v6, v2, s1
	v_add_u32_e32 v6, v6, v5
	s_lshl_b32 s1, s11, 2
	v_mul_lo_u32 v48, v3, s1
	v_add_u32_e32 v48, v48, v4
	global_load_dwordx4 v[8:11], v6, s[4:5]
	v_add_u32_e32 v6, s10, v6
	global_load_dwordx4 v[12:15], v6, s[4:5]
	v_add_u32_e32 v6, s10, v6
	global_load_dwordx4 v[16:19], v6, s[4:5]
	v_add_u32_e32 v6, s10, v6
	global_load_dwordx4 v[20:23], v6, s[4:5]
	v_add_u32_e32 v6, s10, v6
	global_load_dwordx4 v[24:27], v6, s[4:5]
	v_add_u32_e32 v6, s10, v6
	global_load_dwordx4 v[28:31], v6, s[4:5]
	v_add_u32_e32 v6, s10, v6
	global_load_dwordx4 v[32:35], v6, s[4:5]
	v_add_u32_e32 v6, s10, v6
	global_load_dwordx4 v[36:39], v6, s[4:5]
	global_load_dwordx4 v[40:43], v7, s[8:9]
	global_load_dwordx4 v[44:47], v7, s[8:9] offset:16
	s_min_u32 s0, s30, s25
	s_mul_i32 s0, s0, vcc_lo
	s_add_i32 s0, s0, s3
	s_min_u32 s0, s0, vcc_hi
	s_add_i32 s30, s30, 1
	s_cmp_ge_u32 s0, 0x7a00
	s_cselect_b32 s33, 1, 0
	s_mul_i32 s1, s33, 0x7a00
	s_sub_i32 s20, s0, s1
	s_cmp_lt_u32 s20, 0x1000
	s_cbranch_scc1 .Lcv1_win
	s_cmp_lt_u32 s20, 0x1800
	s_cbranch_scc1 .Lcv1_wout
	s_cmp_lt_u32 s20, 0x1a00
	s_cbranch_scc1 .Lcv1_glu
	s_cmp_lt_u32 s20, 0x3a00
	s_cbranch_scc1 .Lcv1_w1
	s_cmp_lt_u32 s20, 0x5a00
	s_cbranch_scc1 .Lcv1_w2
	s_cmp_lt_u32 s20, 0x7200
	s_cbranch_scc1 .Lcv1_qkv

; __device__ __forceinline__ void conv_tile(const float* src, bf16_t* dst, int K, int N, int tile, int lane, const float* gk) {
;     const int tn = N >> 5; const int k0 = (tile / tn) * 64, n0 = (tile % tn) * 32; const int kg = lane & 7, jn = lane >> 3;
;     f32x4 v[8]; const float* sp = src + (size_t)(k0 + 8 * kg) * N + n0 + 4 * jn;
; #pragma unroll
;     for (int r = 0; r < 8; ++r) v[r] = *(const f32x4*)(sp + (size_t)r * N);
;     if (gk) { const f32x4 g0 = *(const f32x4*)(gk + k0 + 8 * kg), g1 = *(const f32x4*)(gk + k0 + 8 * kg + 4);
; #pragma unroll
;         for (int r = 0; r < 4; ++r) { v[r] *= g0[r]; v[4 + r] *= g1[r]; } }
; #pragma unroll
;     for (int i = 0; i < 4; ++i) { u32x4 w; w.x = cvt_pk_bf16(v[0][i], v[1][i]); w.y = cvt_pk_bf16(v[2][i], v[3][i]); w.z = cvt_pk_bf16(v[4][i], v[5][i]); w.w = cvt_pk_bf16(v[6][i], v[7][i]);
;         *(u32x4*)(dst + (size_t)(n0 + 4 * jn + i) * K + k0 + 8 * kg) = w; }
; }
; __device__ __forceinline__ void conv_dispatch(const Params& P, int tile, int lane) {
;     const int j = tile / T_PAIR; int rem = tile % T_PAIR; unsigned char* ws = P.ws;
;     if (rem < T_EVEN) { const int i = 2 * j;
;         if (rem < T_WIN) { conv_tile(P.in[2] + (size_t)j * 2048 * 4096, (bf16_t*)(ws + WS_WIN + j * SZ_WIN), 2048, 4096, rem, lane, P.in[16] + (size_t)i * DM); return; } rem -= T_WIN;
;         if (rem < T_WOUT) { conv_tile(P.in[3] + (size_t)j * 2048 * 2048, (bf16_t*)(ws + WS_WOUT + j * SZ_WOUT), 2048, 2048, rem, lane, nullptr); return; } rem -= T_WOUT;
;         if (rem < T_GLU) { conv_tile(P.in[12] + (size_t)j * 1024 * 1024, (bf16_t*)(ws + WS_GLU + j * SZ_GLU), 1024, 1024, rem, lane, nullptr); return; } rem -= T_GLU;
;         if (rem < T_W1) { conv_tile(P.in[18] + (size_t)i * 2048 * 8192, (bf16_t*)(ws + WS_W1 + i * SZ_W1), 2048, 8192, rem, lane, P.in[17] + (size_t)i * DM); return; } rem -= T_W1;
;         conv_tile(P.in[19] + (size_t)i * 8192 * 2048, (bf16_t*)(ws + WS_W2 + i * SZ_W2), 8192, 2048, rem, lane, nullptr);
;     } else { rem -= T_EVEN; const int i = 2 * j + 1;
;         if (rem < T_QKV) { conv_tile(P.in[13] + (size_t)j * 2048 * 6144, (bf16_t*)(ws + WS_QKV + j * SZ_QKV), 2048, 6144, rem, lane, P.in[16] + (size_t)i * DM); return; } rem -= T_QKV;
;         if (rem < T_WOUT) { conv_tile(P.in[14] + (size_t)j * 2048 * 2048, (bf16_t*)(ws + WS_COUT + j * SZ_WOUT), 2048, 2048, rem, lane, nullptr); return; } rem -= T_WOUT;
.Lcv1_dd:
	s_lshl_b32 s1, s10, 6
	s_mul_i32 s1, s1, s22
	s_lshl_b32 s24, s23, 7
	s_add_u32 s1, s1, s24
	s_add_u32 s4, s4, s1
	s_addc_u32 s5, s5, 0
	s_lshl_b32 s1, s11, 5
	s_mul_i32 s1, s1, s23
	s_lshl_b32 s24, s22, 7
	s_add_u32 s1, s1, s24
	s_add_u32 s76, s6, s1
	s_addc_u32 s77, s7, 0
	s_mov_b32 s78, s11
	s_lshl_b32 s1, s22, 8
	s_cmp_eq_u32 s79, 0
	s_cselect_b32 s8, s4, s8
	s_cselect_b32 s9, s5, s9
	s_cselect_b32 s1, 0, s1
	s_add_u32 s8, s8, s1
	s_addc_u32 s9, s9, 0
	s_lshl_b32 s1, s10, 3
	v_mul_lo_u32 v6, v2, s1
	v_add_u32_e32 v6, v6, v5
	s_lshl_b32 s1, s11, 2
	v_mul_lo_u32 v92, v3, s1
	v_add_u32_e32 v92, v92, v4
	global_load_dwordx4 v[52:55], v6, s[4:5]
	v_add_u32_e32 v6, s10, v6
	global_load_dwordx4 v[56:59], v6, s[4:5]
	v_add_u32_e32 v6, s10, v6
	global_load_dwordx4 v[60:63], v6, s[4:5]
	v_add_u32_e32 v6, s10, v6
	global_load_dwordx4 v[64:67], v6, s[4:5]
	v_add_u32_e32 v6, s10, v6
	global_load_dwordx4 v[68:71], v6, s[4:5]
	v_add_u32_e32 v6, s10, v6
	global_load_dwordx4 v[72:75], v6, s[4:5]
	v_add_u32_e32 v6, s10, v6
	global_load_dwordx4 v[76:79], v6, s[4:5]
	v_add_u32_e32 v6, s10, v6
	global_load_dwordx4 v[80:83], v6, s[4:5]
	global_load_dwordx4 v[84:87], v7, s[8:9]
	global_load_dwordx4 v[88:91], v7, s[8:9] offset:16
	s_min_u32 s0, s30, s25
	s_mul_i32 s0, s0, vcc_lo
	s_add_i32 s0, s0, s3
	s_min_u32 s0, s0, vcc_hi
	s_add_i32 s30, s30, 1
	s_cmp_ge_u32 s0, 0x7a00
	s_cselect_b32 s33, 1, 0
	s_mul_i32 s1, s33, 0x7a00
	s_sub_i32 s20, s0, s1
	s_cmp_lt_u32 s20, 0x1000
	s_cbranch_scc1 .Lcv2_win
	s_cmp_lt_u32 s20, 0x1800
	s_cbranch_scc1 .Lcv2_wout
	s_cmp_lt_u32 s20, 0x1a00
	s_cbranch_scc1 .Lcv2_glu
	s_cmp_lt_u32 s20, 0x3a00
	s_cbranch_scc1 .Lcv2_w1
	s_cmp_lt_u32 s20, 0x5a00
	s_cbranch_scc1 .Lcv2_w2
	s_cmp_lt_u32 s20, 0x7200
	s_cbranch_scc1 .Lcv2_qkv

; __device__ __forceinline__ unsigned cvt_pk_bf16(float lo, float hi) { unsigned r; asm volatile("v_cvt_pk_bf16_f32 %0, %1, %2" : "=v"(r) : "v"(lo), "v"(hi)); return r; }
; __device__ __forceinline__ void conv_tile(const float* src, bf16_t* dst, int K, int N, int tile, int lane, const float* gk) {
;     ...
; #pragma unroll
;     for (int i = 0; i < 4; ++i) { u32x4 w; w.x = cvt_pk_bf16(v[0][i], v[1][i]); w.y = cvt_pk_bf16(v[2][i], v[3][i]); w.z = cvt_pk_bf16(v[4][i], v[5][i]); w.w = cvt_pk_bf16(v[6][i], v[7][i]);
;         *(u32x4*)(dst + (size_t)(n0 + 4 * jn + i) * K + k0 + 8 * kg) = w; }
; __device__ __forceinline__ void conv_dispatch(const Params& P, int tile, int lane) {
;     const int j = tile / T_PAIR; int rem = tile % T_PAIR; unsigned char* ws = P.ws;
;     if (rem < T_EVEN) { const int i = 2 * j;
;         if (rem < T_WIN) { conv_tile(P.in[2] + (size_t)j * 2048 * 4096, (bf16_t*)(ws + WS_WIN + j * SZ_WIN), 2048, 4096, rem, lane, P.in[16] + (size_t)i * DM); return; } rem -= T_WIN;
;         if (rem < T_WOUT) { conv_tile(P.in[3] + (size_t)j * 2048 * 2048, (bf16_t*)(ws + WS_WOUT + j * SZ_WOUT), 2048, 2048, rem, lane, nullptr); return; } rem -= T_WOUT;
;         if (rem < T_GLU) { conv_tile(P.in[12] + (size_t)j * 1024 * 1024, (bf16_t*)(ws + WS_GLU + j * SZ_GLU), 1024, 1024, rem, lane, nullptr); return; } rem -= T_GLU;
;         if (rem < T_W1) { conv_tile(P.in[18] + (size_t)i * 2048 * 8192, (bf16_t*)(ws + WS_W1 + i * SZ_W1), 2048, 8192, rem, lane, P.in[17] + (size_t)i * DM); return; } rem -= T_W1;
;         conv_tile(P.in[19] + (size_t)i * 8192 * 2048, (bf16_t*)(ws + WS_W2 + i * SZ_W2), 8192, 2048, rem, lane, nullptr);
;     } else { rem -= T_EVEN; const int i = 2 * j + 1;
;         if (rem < T_QKV) { conv_tile(P.in[13] + (size_t)j * 2048 * 6144, (bf16_t*)(ws + WS_QKV + j * SZ_QKV), 2048, 6144, rem, lane, P.in[16] + (size_t)i * DM); return; } rem -= T_QKV;
;         if (rem < T_WOUT) { conv_tile(P.in[14] + (size_t)j * 2048 * 2048, (bf16_t*)(ws + WS_COUT + j * SZ_WOUT), 2048, 2048, rem, lane, nullptr); return; } rem -= T_WOUT;
;         if (rem < T_W1) { conv_tile(P.in[18] + (size_t)i * 2048 * 8192, (bf16_t*)(ws + WS_W1 + i * SZ_W1), 2048, 8192, rem, lane, P.in[17] + (size_t)i * DM); return; } rem -= T_W1;
;         conv_tile(P.in[19] + (size_t)i * 8192 * 2048, (bf16_t*)(ws + WS_W2 + i * SZ_W2), 8192, 2048, rem, lane, nullptr);
;     }
; }
.Lcv3_nog:
	v_cvt_pk_bf16_f32 v40, v8, v12
	v_cvt_pk_bf16_f32 v41, v16, v20
	v_cvt_pk_bf16_f32 v42, v24, v28
	v_cvt_pk_bf16_f32 v43, v32, v36
	global_store_dwordx4 v48, v[40:43], s[72:73]
	v_add_u32_e32 v48, s74, v48
	v_cvt_pk_bf16_f32 v44, v9, v13
	v_cvt_pk_bf16_f32 v45, v17, v21
	v_cvt_pk_bf16_f32 v46, v25, v29
	v_cvt_pk_bf16_f32 v47, v33, v37
	global_store_dwordx4 v48, v[44:47], s[72:73]
	v_add_u32_e32 v48, s74, v48
	v_cvt_pk_bf16_f32 v40, v10, v14
	v_cvt_pk_bf16_f32 v41, v18, v22
	v_cvt_pk_bf16_f32 v42, v26, v30
	v_cvt_pk_bf16_f32 v43, v34, v38
	global_store_dwordx4 v48, v[40:43], s[72:73]
	v_add_u32_e32 v48, s74, v48
	v_cvt_pk_bf16_f32 v44, v11, v15
	v_cvt_pk_bf16_f32 v45, v19, v23
	v_cvt_pk_bf16_f32 v46, v27, v31
	v_cvt_pk_bf16_f32 v47, v35, v39
	global_store_dwordx4 v48, v[44:47], s[72:73]
	s_min_u32 s0, s30, s25
	s_mul_i32 s0, s0, vcc_lo
	s_add_i32 s0, s0, s3
	s_min_u32 s0, s0, vcc_hi
	s_add_i32 s30, s30, 1
	s_cmp_ge_u32 s0, 0x7a00
	s_cselect_b32 s33, 1, 0
	s_mul_i32 s1, s33, 0x7a00
	s_sub_i32 s20, s0, s1
	s_cmp_lt_u32 s20, 0x1000
	s_cbranch_scc1 .Lcv4_win
	s_cmp_lt_u32 s20, 0x1800
	s_cbranch_scc1 .Lcv4_wout
	s_cmp_lt_u32 s20, 0x1a00
	s_cbranch_scc1 .Lcv4_glu
	s_cmp_lt_u32 s20, 0x3a00
	s_cbranch_scc1 .Lcv4_w1
	s_cmp_lt_u32 s20, 0x5a00
	s_cbranch_scc1 .Lcv4_w2
	s_cmp_lt_u32 s20, 0x7200
	s_cbranch_scc1 .Lcv4_qkv

; __device__ __forceinline__ unsigned cvt_pk_bf16(float lo, float hi) { unsigned r; asm volatile("v_cvt_pk_bf16_f32 %0, %1, %2" : "=v"(r) : "v"(lo), "v"(hi)); return r; }
; __device__ __forceinline__ void conv_tile(const float* src, bf16_t* dst, int K, int N, int tile, int lane, const float* gk) {
;     ...
; #pragma unroll
;     for (int i = 0; i < 4; ++i) { u32x4 w; w.x = cvt_pk_bf16(v[0][i], v[1][i]); w.y = cvt_pk_bf16(v[2][i], v[3][i]); w.z = cvt_pk_bf16(v[4][i], v[5][i]); w.w = cvt_pk_bf16(v[6][i], v[7][i]);
;         *(u32x4*)(dst + (size_t)(n0 + 4 * jn + i) * K + k0 + 8 * kg) = w; }
; __device__ __forceinline__ void conv_dispatch(const Params& P, int tile, int lane) {
;     const int j = tile / T_PAIR; int rem = tile % T_PAIR; unsigned char* ws = P.ws;
;     if (rem < T_EVEN) { const int i = 2 * j;
;         if (rem < T_WIN) { conv_tile(P.in[2] + (size_t)j * 2048 * 4096, (bf16_t*)(ws + WS_WIN + j * SZ_WIN), 2048, 4096, rem, lane, P.in[16] + (size_t)i * DM); return; } rem -= T_WIN;
;         if (rem < T_WOUT) { conv_tile(P.in[3] + (size_t)j * 2048 * 2048, (bf16_t*)(ws + WS_WOUT + j * SZ_WOUT), 2048, 2048, rem, lane, nullptr); return; } rem -= T_WOUT;
;         if (rem < T_GLU) { conv_tile(P.in[12] + (size_t)j * 1024 * 1024, (bf16_t*)(ws + WS_GLU + j * SZ_GLU), 1024, 1024, rem, lane, nullptr); return; } rem -= T_GLU;
;         if (rem < T_W1) { conv_tile(P.in[18] + (size_t)i * 2048 * 8192, (bf16_t*)(ws + WS_W1 + i * SZ_W1), 2048, 8192, rem, lane, P.in[17] + (size_t)i * DM); return; } rem -= T_W1;
;         conv_tile(P.in[19] + (size_t)i * 8192 * 2048, (bf16_t*)(ws + WS_W2 + i * SZ_W2), 8192, 2048, rem, lane, nullptr);
;     } else { rem -= T_EVEN; const int i = 2 * j + 1;
;         if (rem < T_QKV) { conv_tile(P.in[13] + (size_t)j * 2048 * 6144, (bf16_t*)(ws + WS_QKV + j * SZ_QKV), 2048, 6144, rem, lane, P.in[16] + (size_t)i * DM); return; } rem -= T_QKV;
;         if (rem < T_WOUT) { conv_tile(P.in[14] + (size_t)j * 2048 * 2048, (bf16_t*)(ws + WS_COUT + j * SZ_WOUT), 2048, 2048, rem, lane, nullptr); return; } rem -= T_WOUT;
;         if (rem < T_W1) { conv_tile(P.in[18] + (size_t)i * 2048 * 8192, (bf16_t*)(ws + WS_W1 + i * SZ_W1), 2048, 8192, rem, lane, P.in[17] + (size_t)i * DM); return; } rem -= T_W1;
;         conv_tile(P.in[19] + (size_t)i * 8192 * 2048, (bf16_t*)(ws + WS_W2 + i * SZ_W2), 8192, 2048, rem, lane, nullptr);
;     }
; }
.Lcv5_nog:
	v_cvt_pk_bf16_f32 v84, v52, v56
	v_cvt_pk_bf16_f32 v85, v60, v64
	v_cvt_pk_bf16_f32 v86, v68, v72
	v_cvt_pk_bf16_f32 v87, v76, v80
	global_store_dwordx4 v92, v[84:87], s[76:77]
	v_add_u32_e32 v92, s78, v92
	v_cvt_pk_bf16_f32 v88, v53, v57
	v_cvt_pk_bf16_f32 v89, v61, v65
	v_cvt_pk_bf16_f32 v90, v69, v73
	v_cvt_pk_bf16_f32 v91, v77, v81
	global_store_dwordx4 v92, v[88:91], s[76:77]
	v_add_u32_e32 v92, s78, v92
	v_cvt_pk_bf16_f32 v84, v54, v58
	v_cvt_pk_bf16_f32 v85, v62, v66
	v_cvt_pk_bf16_f32 v86, v70, v74
	v_cvt_pk_bf16_f32 v87, v78, v82
	global_store_dwordx4 v92, v[84:87], s[76:77]
	v_add_u32_e32 v92, s78, v92
	v_cvt_pk_bf16_f32 v88, v55, v59
	v_cvt_pk_bf16_f32 v89, v63, v67
	v_cvt_pk_bf16_f32 v90, v71, v75
	v_cvt_pk_bf16_f32 v91, v79, v83
	global_store_dwordx4 v92, v[88:91], s[76:77]
	s_min_u32 s0, s30, s25
	s_mul_i32 s0, s0, vcc_lo
	s_add_i32 s0, s0, s3
	s_min_u32 s0, s0, vcc_hi
	s_add_i32 s30, s30, 1
	s_cmp_ge_u32 s0, 0x7a00
	s_cselect_b32 s33, 1, 0
	s_mul_i32 s1, s33, 0x7a00
	s_sub_i32 s20, s0, s1
	s_cmp_lt_u32 s20, 0x1000
	s_cbranch_scc1 .Lcv6_win
	s_cmp_lt_u32 s20, 0x1800
	s_cbranch_scc1 .Lcv6_wout
	s_cmp_lt_u32 s20, 0x1a00
	s_cbranch_scc1 .Lcv6_glu
	s_cmp_lt_u32 s20, 0x3a00
	s_cbranch_scc1 .Lcv6_w1
	s_cmp_lt_u32 s20, 0x5a00
	s_cbranch_scc1 .Lcv6_w2
	s_cmp_lt_u32 s20, 0x7200
	s_cbranch_scc1 .Lcv6_qkv

; __device__ __forceinline__ unsigned cvt_pk_bf16(float lo, float hi) { unsigned r; asm volatile("v_cvt_pk_bf16_f32 %0, %1, %2" : "=v"(r) : "v"(lo), "v"(hi)); return r; }
; __device__ __forceinline__ void conv_tile(const float* src, bf16_t* dst, int K, int N, int tile, int lane, const float* gk) {
;     const int tn = N >> 5; const int k0 = (tile / tn) * 64, n0 = (tile % tn) * 32; const int kg = lane & 7, jn = lane >> 3;
;     f32x4 v[8]; const float* sp = src + (size_t)(k0 + 8 * kg) * N + n0 + 4 * jn;
; #pragma unroll
;     for (int r = 0; r < 8; ++r) v[r] = *(const f32x4*)(sp + (size_t)r * N);
;     if (gk) { const f32x4 g0 = *(const f32x4*)(gk + k0 + 8 * kg), g1 = *(const f32x4*)(gk + k0 + 8 * kg + 4);
; #pragma unroll
;         for (int r = 0; r < 4; ++r) { v[r] *= g0[r]; v[4 + r] *= g1[r]; } }
; #pragma unroll
;     for (int i = 0; i < 4; ++i) { u32x4 w; w.x = cvt_pk_bf16(v[0][i], v[1][i]); w.y = cvt_pk_bf16(v[2][i], v[3][i]); w.z = cvt_pk_bf16(v[4][i], v[5][i]); w.w = cvt_pk_bf16(v[6][i], v[7][i]);
;         *(u32x4*)(dst + (size_t)(n0 + 4 * jn + i) * K + k0 + 8 * kg) = w; }
; }
.Lcv6_dd:
	s_lshl_b32 s1, s10, 6
	s_mul_i32 s1, s1, s22
	s_lshl_b32 s24, s23, 7
	s_add_u32 s1, s1, s24
	s_add_u32 s4, s4, s1
	s_addc_u32 s5, s5, 0
	s_lshl_b32 s1, s11, 5
	s_mul_i32 s1, s1, s23
	s_lshl_b32 s24, s22, 7
	s_add_u32 s1, s1, s24
	s_add_u32 s76, s6, s1
	s_addc_u32 s77, s7, 0
	s_mov_b32 s78, s11
	s_lshl_b32 s1, s22, 8
	s_cmp_eq_u32 s79, 0
	s_cselect_b32 s8, s4, s8
	s_cselect_b32 s9, s5, s9
	s_cselect_b32 s1, 0, s1
	s_add_u32 s8, s8, s1
	s_addc_u32 s9, s9, 0
	s_lshl_b32 s1, s10, 3
	v_mul_lo_u32 v6, v2, s1
	v_add_u32_e32 v6, v6, v5
	s_lshl_b32 s1, s11, 2
	v_mul_lo_u32 v92, v3, s1
	v_add_u32_e32 v92, v92, v4
	global_load_dwordx4 v[52:55], v6, s[4:5]
	v_add_u32_e32 v6, s10, v6
	global_load_dwordx4 v[56:59], v6, s[4:5]
	v_add_u32_e32 v6, s10, v6
	global_load_dwordx4 v[60:63], v6, s[4:5]
	v_add_u32_e32 v6, s10, v6
	global_load_dwordx4 v[64:67], v6, s[4:5]
	v_add_u32_e32 v6, s10, v6
	global_load_dwordx4 v[68:71], v6, s[4:5]
	v_add_u32_e32 v6, s10, v6
	global_load_dwordx4 v[72:75], v6, s[4:5]
	v_add_u32_e32 v6, s10, v6
	global_load_dwordx4 v[76:79], v6, s[4:5]
	v_add_u32_e32 v6, s10, v6
	global_load_dwordx4 v[80:83], v6, s[4:5]
	global_load_dwordx4 v[84:87], v7, s[8:9]
	global_load_dwordx4 v[88:91], v7, s[8:9] offset:16
	s_mov_b32 s38, 0
	s_cmp_eq_u32 s39, 0
	s_cbranch_scc1 .Lcv_tail

; __device__ __forceinline__ unsigned cvt_pk_bf16(float lo, float hi) { unsigned r; asm volatile("v_cvt_pk_bf16_f32 %0, %1, %2" : "=v"(r) : "v"(lo), "v"(hi)); return r; }
; __device__ __forceinline__ void conv_tile(const float* src, bf16_t* dst, int K, int N, int tile, int lane, const float* gk) {
;     ...
; #pragma unroll
;     for (int i = 0; i < 4; ++i) { u32x4 w; w.x = cvt_pk_bf16(v[0][i], v[1][i]); w.y = cvt_pk_bf16(v[2][i], v[3][i]); w.z = cvt_pk_bf16(v[4][i], v[5][i]); w.w = cvt_pk_bf16(v[6][i], v[7][i]);
;         *(u32x4*)(dst + (size_t)(n0 + 4 * jn + i) * K + k0 + 8 * kg) = w; }
; __device__ __forceinline__ void conv_dispatch(const Params& P, int tile, int lane) {
;     const int j = tile / T_PAIR; int rem = tile % T_PAIR; unsigned char* ws = P.ws;
;     if (rem < T_EVEN) { const int i = 2 * j;
;         if (rem < T_WIN) { conv_tile(P.in[2] + (size_t)j * 2048 * 4096, (bf16_t*)(ws + WS_WIN + j * SZ_WIN), 2048, 4096, rem, lane, P.in[16] + (size_t)i * DM); return; } rem -= T_WIN;
;         if (rem < T_WOUT) { conv_tile(P.in[3] + (size_t)j * 2048 * 2048, (bf16_t*)(ws + WS_WOUT + j * SZ_WOUT), 2048, 2048, rem, lane, nullptr); return; } rem -= T_WOUT;
;         if (rem < T_GLU) { conv_tile(P.in[12] + (size_t)j * 1024 * 1024, (bf16_t*)(ws + WS_GLU + j * SZ_GLU), 1024, 1024, rem, lane, nullptr); return; } rem -= T_GLU;
;         if (rem < T_W1) { conv_tile(P.in[18] + (size_t)i * 2048 * 8192, (bf16_t*)(ws + WS_W1 + i * SZ_W1), 2048, 8192, rem, lane, P.in[17] + (size_t)i * DM); return; } rem -= T_W1;
;         conv_tile(P.in[19] + (size_t)i * 8192 * 2048, (bf16_t*)(ws + WS_W2 + i * SZ_W2), 8192, 2048, rem, lane, nullptr);
;     } else { rem -= T_EVEN; const int i = 2 * j + 1;
;         if (rem < T_QKV) { conv_tile(P.in[13] + (size_t)j * 2048 * 6144, (bf16_t*)(ws + WS_QKV + j * SZ_QKV), 2048, 6144, rem, lane, P.in[16] + (size_t)i * DM); return; } rem -= T_QKV;
;         if (rem < T_WOUT) { conv_tile(P.in[14] + (size_t)j * 2048 * 2048, (bf16_t*)(ws + WS_COUT + j * SZ_WOUT), 2048, 2048, rem, lane, nullptr); return; } rem -= T_WOUT;
;         if (rem < T_W1) { conv_tile(P.in[18] + (size_t)i * 2048 * 8192, (bf16_t*)(ws + WS_W1 + i * SZ_W1), 2048, 8192, rem, lane, P.in[17] + (size_t)i * DM); return; } rem -= T_W1;
;         conv_tile(P.in[19] + (size_t)i * 8192 * 2048, (bf16_t*)(ws + WS_W2 + i * SZ_W2), 8192, 2048, rem, lane, nullptr);
;     }
; }
.Lcv7_nog:
	v_cvt_pk_bf16_f32 v128, v96, v100
	v_cvt_pk_bf16_f32 v129, v104, v108
	v_cvt_pk_bf16_f32 v130, v112, v116
	v_cvt_pk_bf16_f32 v131, v120, v124
	global_store_dwordx4 v136, v[128:131], s[80:81]
	v_add_u32_e32 v136, s82, v136
	v_cvt_pk_bf16_f32 v132, v97, v101
	v_cvt_pk_bf16_f32 v133, v105, v109
	v_cvt_pk_bf16_f32 v134, v113, v117
	v_cvt_pk_bf16_f32 v135, v121, v125
	global_store_dwordx4 v136, v[132:135], s[80:81]
	v_add_u32_e32 v136, s82, v136
	v_cvt_pk_bf16_f32 v128, v98, v102
	v_cvt_pk_bf16_f32 v129, v106, v110
	v_cvt_pk_bf16_f32 v130, v114, v118
	v_cvt_pk_bf16_f32 v131, v122, v126
	global_store_dwordx4 v136, v[128:131], s[80:81]
	v_add_u32_e32 v136, s82, v136
	v_cvt_pk_bf16_f32 v132, v99, v103
	v_cvt_pk_bf16_f32 v133, v107, v111
	v_cvt_pk_bf16_f32 v134, v115, v119
	v_cvt_pk_bf16_f32 v135, v123, v127
	global_store_dwordx4 v136, v[132:135], s[80:81]
	s_min_u32 s0, s30, s25
	s_mul_i32 s0, s0, vcc_lo
	s_add_i32 s0, s0, s3
	s_min_u32 s0, s0, vcc_hi
	s_add_i32 s30, s30, 1
	s_cmp_ge_u32 s0, 0x7a00
	s_cselect_b32 s33, 1, 0
	s_mul_i32 s1, s33, 0x7a00
	s_sub_i32 s20, s0, s1
	s_cmp_lt_u32 s20, 0x1000
	s_cbranch_scc1 .Lcv8_win
	s_cmp_lt_u32 s20, 0x1800
	s_cbranch_scc1 .Lcv8_wout
	s_cmp_lt_u32 s20, 0x1a00
	s_cbranch_scc1 .Lcv8_glu
	s_cmp_lt_u32 s20, 0x3a00
	s_cbranch_scc1 .Lcv8_w1
	s_cmp_lt_u32 s20, 0x5a00
	s_cbranch_scc1 .Lcv8_w2
	s_cmp_lt_u32 s20, 0x7200
	s_cbranch_scc1 .Lcv8_qkv

; __device__ __forceinline__ unsigned cvt_pk_bf16(float lo, float hi) { unsigned r; asm volatile("v_cvt_pk_bf16_f32 %0, %1, %2" : "=v"(r) : "v"(lo), "v"(hi)); return r; }
; __device__ __forceinline__ void conv_tile(const float* src, bf16_t* dst, int K, int N, int tile, int lane, const float* gk) {
;     const int tn = N >> 5; const int k0 = (tile / tn) * 64, n0 = (tile % tn) * 32; const int kg = lane & 7, jn = lane >> 3;
;     f32x4 v[8]; const float* sp = src + (size_t)(k0 + 8 * kg) * N + n0 + 4 * jn;
; #pragma unroll
;     for (int r = 0; r < 8; ++r) v[r] = *(const f32x4*)(sp + (size_t)r * N);
;     if (gk) { const f32x4 g0 = *(const f32x4*)(gk + k0 + 8 * kg), g1 = *(const f32x4*)(gk + k0 + 8 * kg + 4);
; #pragma unroll
;         for (int r = 0; r < 4; ++r) { v[r] *= g0[r]; v[4 + r] *= g1[r]; } }
; #pragma unroll
;     for (int i = 0; i < 4; ++i) { u32x4 w; w.x = cvt_pk_bf16(v[0][i], v[1][i]); w.y = cvt_pk_bf16(v[2][i], v[3][i]); w.z = cvt_pk_bf16(v[4][i], v[5][i]); w.w = cvt_pk_bf16(v[6][i], v[7][i]);
;         *(u32x4*)(dst + (size_t)(n0 + 4 * jn + i) * K + k0 + 8 * kg) = w; }
; }
.Lcv12_dd:
	s_lshl_b32 s1, s10, 6
	s_mul_i32 s1, s1, s22
	s_lshl_b32 s24, s23, 7
	s_add_u32 s1, s1, s24
	s_add_u32 s4, s4, s1
	s_addc_u32 s5, s5, 0
	s_lshl_b32 s1, s11, 5
	s_mul_i32 s1, s1, s23
	s_lshl_b32 s24, s22, 7
	s_add_u32 s1, s1, s24
	s_add_u32 s76, s6, s1
	s_addc_u32 s77, s7, 0
	s_mov_b32 s78, s11
	s_lshl_b32 s1, s22, 8
	s_cmp_eq_u32 s79, 0
	s_cselect_b32 s8, s4, s8
	s_cselect_b32 s9, s5, s9
	s_cselect_b32 s1, 0, s1
	s_add_u32 s8, s8, s1
	s_addc_u32 s9, s9, 0
	s_lshl_b32 s1, s10, 3
	v_mul_lo_u32 v6, v2, s1
	v_add_u32_e32 v6, v6, v5
	s_lshl_b32 s1, s11, 2
	v_mul_lo_u32 v92, v3, s1
	v_add_u32_e32 v92, v92, v4
	global_load_dwordx4 v[52:55], v6, s[4:5]
	v_add_u32_e32 v6, s10, v6
	global_load_dwordx4 v[56:59], v6, s[4:5]
	v_add_u32_e32 v6, s10, v6
	global_load_dwordx4 v[60:63], v6, s[4:5]
	v_add_u32_e32 v6, s10, v6
	global_load_dwordx4 v[64:67], v6, s[4:5]
	v_add_u32_e32 v6, s10, v6
	global_load_dwordx4 v[68:71], v6, s[4:5]
	v_add_u32_e32 v6, s10, v6
	global_load_dwordx4 v[72:75], v6, s[4:5]
	v_add_u32_e32 v6, s10, v6
	global_load_dwordx4 v[76:79], v6, s[4:5]
	v_add_u32_e32 v6, s10, v6
	global_load_dwordx4 v[80:83], v6, s[4:5]
	global_load_dwordx4 v[84:87], v7, s[8:9]
	global_load_dwordx4 v[88:91], v7, s[8:9] offset:16
	s_add_i32 s38, s38, 1
	s_cmp_lt_u32 s38, s39
	s_cbranch_scc1 .Lcv_loop
.Lcv_tail:
	s_waitcnt vmcnt(28)
	s_cmp_eq_u32 s83, 0
	s_cbranch_scc1 .Lcv13_nog
	v_mul_f32_e32 v96, v128, v96
	v_mul_f32_e32 v97, v128, v97
	v_mul_f32_e32 v98, v128, v98
	v_mul_f32_e32 v99, v128, v99
	v_mul_f32_e32 v100, v129, v100
	v_mul_f32_e32 v101, v129, v101
	v_mul_f32_e32 v102, v129, v102
	v_mul_f32_e32 v103, v129, v103
	v_mul_f32_e32 v104, v130, v104
	v_mul_f32_e32 v105, v130, v105
	v_mul_f32_e32 v106, v130, v106
	v_mul_f32_e32 v107, v130, v107
	v_mul_f32_e32 v108, v131, v108
	v_mul_f32_e32 v109, v131, v109
	v_mul_f32_e32 v110, v131, v110
	v_mul_f32_e32 v111, v131, v111
	v_mul_f32_e32 v112, v132, v112
	v_mul_f32_e32 v113, v132, v113
	v_mul_f32_e32 v114, v132, v114
	v_mul_f32_e32 v115, v132, v115
	v_mul_f32_e32 v116, v133, v116
	v_mul_f32_e32 v117, v133, v117
	v_mul_f32_e32 v118, v133, v118
	v_mul_f32_e32 v119, v133, v119
	v_mul_f32_e32 v120, v134, v120
	v_mul_f32_e32 v121, v134, v121
	v_mul_f32_e32 v122, v134, v122
	v_mul_f32_e32 v123, v134, v123
	v_mul_f32_e32 v124, v135, v124
	v_mul_f32_e32 v125, v135, v125
	v_mul_f32_e32 v126, v135, v126
	v_mul_f32_e32 v127, v135, v127
.Lcv13_nog:
	v_cvt_pk_bf16_f32 v128, v96, v100
	v_cvt_pk_bf16_f32 v129, v104, v108
	v_cvt_pk_bf16_f32 v130, v112, v116
	v_cvt_pk_bf16_f32 v131, v120, v124
	global_store_dwordx4 v136, v[128:131], s[80:81]
	v_add_u32_e32 v136, s82, v136
	v_cvt_pk_bf16_f32 v132, v97, v101
	v_cvt_pk_bf16_f32 v133, v105, v109
	v_cvt_pk_bf16_f32 v134, v113, v117
	v_cvt_pk_bf16_f32 v135, v121, v125
	global_store_dwordx4 v136, v[132:135], s[80:81]
	v_add_u32_e32 v136, s82, v136
	v_cvt_pk_bf16_f32 v128, v98, v102
	v_cvt_pk_bf16_f32 v129, v106, v110
	v_cvt_pk_bf16_f32 v130, v114, v118
	v_cvt_pk_bf16_f32 v131, v122, v126
	global_store_dwordx4 v136, v[128:131], s[80:81]
	v_add_u32_e32 v136, s82, v136
	v_cvt_pk_bf16_f32 v132, v99, v103
	v_cvt_pk_bf16_f32 v133, v107, v111
	v_cvt_pk_bf16_f32 v134, v115, v119
	v_cvt_pk_bf16_f32 v135, v123, v127
	global_store_dwordx4 v136, v[132:135], s[80:81]
	s_waitcnt vmcnt(0)
	s_cmp_eq_u32 s75, 0
	s_cbranch_scc1 .Lcv14_nog
	v_mul_f32_e32 v8, v40, v8
	v_mul_f32_e32 v9, v40, v9
	v_mul_f32_e32 v10, v40, v10
	v_mul_f32_e32 v11, v40, v11
	v_mul_f32_e32 v12, v41, v12
	v_mul_f32_e32 v13, v41, v13
	v_mul_f32_e32 v14, v41, v14
	v_mul_f32_e32 v15, v41, v15
	v_mul_f32_e32 v16, v42, v16
	v_mul_f32_e32 v17, v42, v17
	v_mul_f32_e32 v18, v42, v18
	v_mul_f32_e32 v19, v42, v19
	v_mul_f32_e32 v20, v43, v20
	v_mul_f32_e32 v21, v43, v21
	v_mul_f32_e32 v22, v43, v22
	v_mul_f32_e32 v23, v43, v23
	v_mul_f32_e32 v24, v44, v24
	v_mul_f32_e32 v25, v44, v25
	v_mul_f32_e32 v26, v44, v26
	v_mul_f32_e32 v27, v44, v27
	v_mul_f32_e32 v28, v45, v28
	v_mul_f32_e32 v29, v45, v29
	v_mul_f32_e32 v30, v45, v30
	v_mul_f32_e32 v31, v45, v31
	v_mul_f32_e32 v32, v46, v32
	v_mul_f32_e32 v33, v46, v33
	v_mul_f32_e32 v34, v46, v34
	v_mul_f32_e32 v35, v46, v35
	v_mul_f32_e32 v36, v47, v36
	v_mul_f32_e32 v37, v47, v37
	v_mul_f32_e32 v38, v47, v38
	v_mul_f32_e32 v39, v47, v39

; __device__ __forceinline__ unsigned cvt_pk_bf16(float lo, float hi) { unsigned r; asm volatile("v_cvt_pk_bf16_f32 %0, %1, %2" : "=v"(r) : "v"(lo), "v"(hi)); return r; }
; __device__ __forceinline__ void s5_gen(LAS unsigned char* lds, const Params& P, int j, int g) {
;     ...
;     for (int ch = tid; ch < 256 * 64; ch += NTHR) {
;         const int row = ch >> 6, kc = (ch & 63) * 8, dir = row >> 7, im = (row >> 6) & 1, pp = row & 63, t = kc >> 4, c0 = kc & 15; const int ex = (dir == 0) ? (31 - t) : t;
;         const f32x2 w = pw[(dir * 33 + ex) * 64 + pp]; float v[8];
; #pragma unroll
;         for (int e = 0; e < 8; ++e) { const f32x2 b = bb[(dir * 64 + pp) * 16 + c0 + e]; v[e] = im ? (w.x * b.y + w.y * b.x) : (w.x * b.x - w.y * b.y); }
;         u32x4 wv; wv.x = cvt_pk_bf16(v[0], v[1]); wv.y = cvt_pk_bf16(v[2], v[3]); wv.z = cvt_pk_bf16(v[4], v[5]); wv.w = cvt_pk_bf16(v[6], v[7]);
;         *(u32x4*)(B1 + (size_t)row * 512 + kc) = wv;
;     }
; __global__ void __launch_bounds__(NTHR) hybrid_encoder_fwd(Params P) {
;     ...
;         for (int it = bid; it < 128; it += G) { s5_gen(lds, P, it >> 6, it & 63);
;         }
;         {
;             constexpr int PB_PAIR = (T_PAIR - T_W1 - T_W2) / 4, NBATCH = 2 * PB_PAIR, NB1 = 11712;
;     ...
;             if (bid >= 128) for (int bt = (bid - 128) * 8 + wid; bt < NB1; bt += (G - 128) * 8) {
; #pragma unroll 1
;                 for (int q = 0; q < 4; ++q) conv_dispatch(P, PREP_TILE(bt) + q, lane); }
;             for (int bt = NB1 + bid * 8 + wid; bt < NBATCH; bt += G * 8) {
; #pragma unroll 1
;                 for (int q = 0; q < 4; ++q) conv_dispatch(P, PREP_TILE(bt) + q, lane); }
.LBB0_116:
	s_movk_i32 s6, 0x2000
	v_lshrrev_b32_e32 v7, 13, v6
	v_and_b32_e32 v8, 63, v4
	v_and_b32_e32 v9, 8, v5
	v_cmp_gt_u32_e32 vcc, s6, v6
	v_and_b32_e32 v12, 0x2000, v6
	v_mul_u32_u24_e32 v7, 33, v7
	v_cndmask_b32_e32 v11, v66, v67, vcc
	v_lshlrev_b32_e32 v14, 3, v8
	v_add_u32_e32 v12, 0, v12
	v_lshlrev_b32_e32 v8, 7, v8
	v_lshlrev_b32_e32 v9, 3, v9
	v_add_u32_e32 v13, 0x200, v6
	s_movk_i32 s6, 0x3dff
	v_add_lshl_u32 v7, v11, v7, 9
	v_add3_u32 v11, v12, v8, v9
	v_and_b32_e32 v86, 0x1000, v6
	v_cmp_lt_u32_e32 vcc, s6, v6
	v_mov_b32_e32 v6, v13
	v_add3_u32 v7, 0, v7, v14
	ds_read_b128 v[12:15], v11 offset:33808
	ds_read_b128 v[16:19], v11 offset:33824
	ds_read_b128 v[20:23], v11 offset:33840
	ds_read_b64 v[8:9], v7
	ds_read_b128 v[24:27], v11 offset:33792
	s_or_b64 s[0:1], vcc, s[0:1]
	v_cmp_eq_u32_e32 vcc, 0, v86
	s_mov_b64 s[6:7], 0x2000
	s_waitcnt lgkmcnt(1)
	v_pk_mul_f32 v[32:33], v[8:9], v[12:13] op_sel:[0,1] op_sel_hi:[1,0]
	v_pk_mul_f32 v[12:13], v[8:9], v[12:13]
	v_pk_mul_f32 v[34:35], v[8:9], v[14:15] op_sel:[0,1] op_sel_hi:[1,0]
	v_pk_mul_f32 v[14:15], v[8:9], v[14:15]
	v_pk_mul_f32 v[56:57], v[8:9], v[16:17] op_sel:[0,1] op_sel_hi:[1,0]
	v_pk_mul_f32 v[16:17], v[8:9], v[16:17]
	v_pk_mul_f32 v[58:59], v[8:9], v[18:19] op_sel:[0,1] op_sel_hi:[1,0]
	v_pk_mul_f32 v[18:19], v[8:9], v[18:19]
	s_waitcnt lgkmcnt(0)
	v_pk_mul_f32 v[28:29], v[8:9], v[24:25] op_sel:[0,1] op_sel_hi:[1,0]
	v_pk_mul_f32 v[24:25], v[8:9], v[24:25]
	v_pk_mul_f32 v[30:31], v[8:9], v[26:27] op_sel:[0,1] op_sel_hi:[1,0]
	v_pk_mul_f32 v[26:27], v[8:9], v[26:27]
	v_pk_mul_f32 v[60:61], v[8:9], v[20:21] op_sel:[0,1] op_sel_hi:[1,0]
	v_pk_mul_f32 v[20:21], v[8:9], v[20:21]
	v_pk_mul_f32 v[84:85], v[8:9], v[22:23] op_sel:[0,1] op_sel_hi:[1,0]
	v_pk_mul_f32 v[8:9], v[8:9], v[22:23]
	v_sub_f32_e32 v12, v12, v13
	v_add_f32_e32 v13, v34, v35
	v_sub_f32_e32 v14, v14, v15
	v_add_f32_e32 v15, v56, v57
	v_sub_f32_e32 v16, v16, v17
	v_add_f32_e32 v17, v58, v59
	v_sub_f32_e32 v18, v18, v19
	v_add_f32_e32 v7, v28, v29
	v_sub_f32_e32 v11, v24, v25
	v_add_f32_e32 v22, v30, v31
	v_sub_f32_e32 v23, v26, v27
	v_add_f32_e32 v24, v32, v33
	v_add_f32_e32 v19, v60, v61
	v_sub_f32_e32 v20, v20, v21
	v_add_f32_e32 v21, v84, v85
	v_sub_f32_e32 v8, v8, v9
	v_cndmask_b32_e32 v13, v13, v14, vcc
	v_cndmask_b32_e32 v14, v15, v16, vcc
	v_cndmask_b32_e32 v15, v17, v18, vcc
	v_add_u32_e32 v5, 0x1000, v5
	v_add_u32_e32 v4, 8, v4
	v_cndmask_b32_e32 v7, v7, v11, vcc
	v_cndmask_b32_e32 v9, v22, v23, vcc
	v_cndmask_b32_e32 v11, v24, v12, vcc
	v_cndmask_b32_e32 v16, v19, v20, vcc
	v_cndmask_b32_e32 v8, v21, v8, vcc
	v_cvt_pk_bf16_f32 v12, v7, v9
	v_cvt_pk_bf16_f32 v13, v11, v13
	v_cvt_pk_bf16_f32 v14, v14, v15
	v_cvt_pk_bf16_f32 v15, v16, v8
	global_store_dwordx4 v[2:3], v[12:15], off
	v_lshl_add_u64 v[2:3], v[2:3], 0, s[6:7]
	s_andn2_b64 exec, exec, s[0:1]
	s_cbranch_execnz .LBB0_116
	s_or_b64 exec, exec, s[0:1]
	s_add_i32 s29, s29, s94
	s_add_i32 s28, s28, s94
	s_cmpk_gt_i32 s29, 0x7f
	s_barrier
	s_cbranch_scc0 .LBB0_57
	v_readlane_b32 s22, v253, 16
	v_readlane_b32 s23, v253, 17
	s_add_i32 s3, s22, 0xac00
	s_mov_b32 s25, 0
	s_mov_b32 s39, 0
	s_mov_b32 vcc_lo, 0x400
	s_mov_b32 vcc_hi, -1
	s_branch .Lcv_entry

; __device__ __forceinline__ void conv_dispatch(const Params& P, int tile, int lane) {
;     const int j = tile / T_PAIR; int rem = tile % T_PAIR; unsigned char* ws = P.ws;
;     if (rem < T_EVEN) { const int i = 2 * j;
;         if (rem < T_WIN) { conv_tile(P.in[2] + (size_t)j * 2048 * 4096, (bf16_t*)(ws + WS_WIN + j * SZ_WIN), 2048, 4096, rem, lane, P.in[16] + (size_t)i * DM); return; } rem -= T_WIN;
;         if (rem < T_WOUT) { conv_tile(P.in[3] + (size_t)j * 2048 * 2048, (bf16_t*)(ws + WS_WOUT + j * SZ_WOUT), 2048, 2048, rem, lane, nullptr); return; } rem -= T_WOUT;
;         if (rem < T_GLU) { conv_tile(P.in[12] + (size_t)j * 1024 * 1024, (bf16_t*)(ws + WS_GLU + j * SZ_GLU), 1024, 1024, rem, lane, nullptr); return; } rem -= T_GLU;
;         if (rem < T_W1) { conv_tile(P.in[18] + (size_t)i * 2048 * 8192, (bf16_t*)(ws + WS_W1 + i * SZ_W1), 2048, 8192, rem, lane, P.in[17] + (size_t)i * DM); return; } rem -= T_W1;
;         conv_tile(P.in[19] + (size_t)i * 8192 * 2048, (bf16_t*)(ws + WS_W2 + i * SZ_W2), 8192, 2048, rem, lane, nullptr);
;     } else { rem -= T_EVEN; const int i = 2 * j + 1;
;         if (rem < T_QKV) { conv_tile(P.in[13] + (size_t)j * 2048 * 6144, (bf16_t*)(ws + WS_QKV + j * SZ_QKV), 2048, 6144, rem, lane, P.in[16] + (size_t)i * DM); return; } rem -= T_QKV;
;         if (rem < T_WOUT) { conv_tile(P.in[14] + (size_t)j * 2048 * 2048, (bf16_t*)(ws + WS_COUT + j * SZ_WOUT), 2048, 2048, rem, lane, nullptr); return; } rem -= T_WOUT;
;         if (rem < T_W1) { conv_tile(P.in[18] + (size_t)i * 2048 * 8192, (bf16_t*)(ws + WS_W1 + i * SZ_W1), 2048, 8192, rem, lane, P.in[17] + (size_t)i * DM); return; } rem -= T_W1;
;         conv_tile(P.in[19] + (size_t)i * 8192 * 2048, (bf16_t*)(ws + WS_W2 + i * SZ_W2), 8192, 2048, rem, lane, nullptr);
;     }
; }
; __global__ void __launch_bounds__(NTHR) hybrid_encoder_fwd(Params P) {
;     ...
;                     attn_a_phase(lds, bid - 64, 192, 8, Qb, Kb, Vb, P.in[1], NUM, ML);
.LBB0_572:
	v_writelane_b32 v255, s0, 16
	v_writelane_b32 v255, s1, 17
	v_writelane_b32 v255, s3, 18
	v_writelane_b32 v255, s4, 19
	v_writelane_b32 v255, s5, 20
	v_writelane_b32 v255, s6, 21
	v_writelane_b32 v255, s7, 22
	v_writelane_b32 v255, s8, 23
	v_writelane_b32 v255, s9, 24
	v_writelane_b32 v255, s10, 25
	v_writelane_b32 v255, s11, 26
	v_writelane_b32 v255, s12, 27
	v_writelane_b32 v255, s13, 28
	v_writelane_b32 v255, s14, 29
	v_writelane_b32 v255, s15, 30
	v_writelane_b32 v255, s16, 31
	v_writelane_b32 v255, s17, 32
	v_writelane_b32 v255, s18, 33
	v_writelane_b32 v255, s19, 34
	v_writelane_b32 v255, s20, 35
	v_writelane_b32 v255, s21, 36
	v_writelane_b32 v255, s22, 37
	v_writelane_b32 v255, s23, 38
	v_writelane_b32 v255, s24, 39
	v_writelane_b32 v255, s25, 40
	v_writelane_b32 v255, s30, 41
	v_writelane_b32 v255, s33, 42
	v_writelane_b32 v255, s38, 43
	v_writelane_b32 v255, s39, 44
	v_writelane_b32 v255, s72, 45
	v_writelane_b32 v255, s73, 46
	v_writelane_b32 v255, s74, 47
	v_writelane_b32 v255, s75, 48
	v_writelane_b32 v255, s76, 49
	v_writelane_b32 v255, s77, 50
	v_writelane_b32 v255, s78, 51
	v_writelane_b32 v255, s79, 52
	v_writelane_b32 v255, s80, 53
	v_writelane_b32 v255, s81, 54
	v_writelane_b32 v255, s82, 55
	v_writelane_b32 v255, s83, 56
	v_writelane_b32 v255, s86, 57
	v_writelane_b32 v255, s87, 58
	v_writelane_b32 v255, s88, 59
	v_writelane_b32 v255, s89, 60
	v_writelane_b32 v255, vcc_lo, 61
	v_writelane_b32 v255, vcc_hi, 62
	v_readlane_b32 s0, v252, 25
	v_readfirstlane_b32 s1, v200
	s_lshr_b32 s1, s1, 6
	s_sub_i32 s3, s2, 64
	s_lshl_b32 s3, s3, 3
	s_add_i32 s3, s3, s1
	s_mov_b32 s20, 0xb000
	s_mov_b32 s21, 0xd400
	s_mov_b32 s22, 0xd3ff
	s_mov_b32 s23, 0xf3ff
	s_cmp_eq_u32 s0, 0
	s_cselect_b32 s20, s20, s21
	s_cselect_b32 vcc_hi, s22, s23
	s_add_i32 s3, s3, s20
	s_mov_b32 vcc_lo, 0x600
	s_mov_b32 s25, 5
	s_mov_b32 s39, 1
	v_readlane_b32 s86, v255, 0
	v_readlane_b32 s87, v255, 1
	v_readlane_b32 s88, v255, 2
	v_readlane_b32 s89, v255, 3
	v_readlane_b32 s12, v255, 4
	v_readlane_b32 s13, v255, 5
	v_readlane_b32 s14, v255, 6
	v_readlane_b32 s15, v255, 7
	v_readlane_b32 s16, v255, 8
	v_readlane_b32 s17, v255, 9
	v_readlane_b32 s18, v255, 10
	v_readlane_b32 s19, v255, 11
.Lcw_entry:
	s_waitcnt lgkmcnt(0)
	v_and_b32_e32 v2, 7, v201
	v_lshrrev_b32_e32 v3, 3, v201
	v_lshlrev_b32_e32 v4, 4, v2
	v_lshlrev_b32_e32 v5, 4, v3
	v_lshlrev_b32_e32 v7, 5, v2
	s_mov_b32 s30, 0
	s_min_u32 s0, s30, s25
	s_mul_i32 s0, s0, vcc_lo
	s_add_i32 s0, s0, s3
	s_min_u32 s0, s0, vcc_hi
	s_add_i32 s30, s30, 1
	s_cmp_ge_u32 s0, 0x7a00
	s_cselect_b32 s33, 1, 0
	s_mul_i32 s1, s33, 0x7a00
	s_sub_i32 s20, s0, s1
	s_cmp_lt_u32 s20, 0x1000
	s_cbranch_scc1 .Lcw15_win
	s_cmp_lt_u32 s20, 0x1800
	s_cbranch_scc1 .Lcw15_wout
	s_cmp_lt_u32 s20, 0x1a00
	s_cbranch_scc1 .Lcw15_glu
	s_cmp_lt_u32 s20, 0x3a00
	s_cbranch_scc1 .Lcw15_w1
	s_cmp_lt_u32 s20, 0x5a00
	s_cbranch_scc1 .Lcw15_w2
	s_cmp_lt_u32 s20, 0x7200
	s_cbranch_scc1 .Lcw15_qkv

; __device__ __forceinline__ unsigned cvt_pk_bf16(float lo, float hi) { unsigned r; asm volatile("v_cvt_pk_bf16_f32 %0, %1, %2" : "=v"(r) : "v"(lo), "v"(hi)); return r; }
; __device__ __forceinline__ void conv_tile(const float* src, bf16_t* dst, int K, int N, int tile, int lane, const float* gk) {
;     const int tn = N >> 5; const int k0 = (tile / tn) * 64, n0 = (tile % tn) * 32; const int kg = lane & 7, jn = lane >> 3;
;     f32x4 v[8]; const float* sp = src + (size_t)(k0 + 8 * kg) * N + n0 + 4 * jn;
; #pragma unroll
;     for (int r = 0; r < 8; ++r) v[r] = *(const f32x4*)(sp + (size_t)r * N);
;     if (gk) { const f32x4 g0 = *(const f32x4*)(gk + k0 + 8 * kg), g1 = *(const f32x4*)(gk + k0 + 8 * kg + 4);
; #pragma unroll
;         for (int r = 0; r < 4; ++r) { v[r] *= g0[r]; v[4 + r] *= g1[r]; } }
; #pragma unroll
;     for (int i = 0; i < 4; ++i) { u32x4 w; w.x = cvt_pk_bf16(v[0][i], v[1][i]); w.y = cvt_pk_bf16(v[2][i], v[3][i]); w.z = cvt_pk_bf16(v[4][i], v[5][i]); w.w = cvt_pk_bf16(v[6][i], v[7][i]);
;         *(u32x4*)(dst + (size_t)(n0 + 4 * jn + i) * K + k0 + 8 * kg) = w; }
; }
.Lcw27_dd:
	s_lshl_b32 s1, s10, 6
	s_mul_i32 s1, s1, s22
	s_lshl_b32 s24, s23, 7
	s_add_u32 s1, s1, s24
	s_add_u32 s4, s4, s1
	s_addc_u32 s5, s5, 0
	s_lshl_b32 s1, s11, 5
	s_mul_i32 s1, s1, s23
	s_lshl_b32 s24, s22, 7
	s_add_u32 s1, s1, s24
	s_add_u32 s76, s6, s1
	s_addc_u32 s77, s7, 0
	s_mov_b32 s78, s11
	s_lshl_b32 s1, s22, 8
	s_cmp_eq_u32 s79, 0
	s_cselect_b32 s8, s4, s8
	s_cselect_b32 s9, s5, s9
	s_cselect_b32 s1, 0, s1
	s_add_u32 s8, s8, s1
	s_addc_u32 s9, s9, 0
	s_lshl_b32 s1, s10, 3
	v_mul_lo_u32 v6, v2, s1
	v_add_u32_e32 v6, v6, v5
	s_lshl_b32 s1, s11, 2
	v_mul_lo_u32 v92, v3, s1
	v_add_u32_e32 v92, v92, v4
	global_load_dwordx4 v[52:55], v6, s[4:5]
	v_add_u32_e32 v6, s10, v6
	global_load_dwordx4 v[56:59], v6, s[4:5]
	v_add_u32_e32 v6, s10, v6
	global_load_dwordx4 v[60:63], v6, s[4:5]
	v_add_u32_e32 v6, s10, v6
	global_load_dwordx4 v[64:67], v6, s[4:5]
	v_add_u32_e32 v6, s10, v6
	global_load_dwordx4 v[68:71], v6, s[4:5]
	v_add_u32_e32 v6, s10, v6
	global_load_dwordx4 v[72:75], v6, s[4:5]
	v_add_u32_e32 v6, s10, v6
	global_load_dwordx4 v[76:79], v6, s[4:5]
	v_add_u32_e32 v6, s10, v6
	global_load_dwordx4 v[80:83], v6, s[4:5]
	global_load_dwordx4 v[84:87], v7, s[8:9]
	global_load_dwordx4 v[88:91], v7, s[8:9] offset:16
	s_add_i32 s38, s38, 1
	s_cmp_lt_u32 s38, s39
	s_cbranch_scc1 .Lcw_loop
.Lcw_tail:
	s_waitcnt vmcnt(28)
	s_cmp_eq_u32 s83, 0
	s_cbranch_scc1 .Lcw28_nog
	v_mul_f32_e32 v96, v128, v96
	v_mul_f32_e32 v97, v128, v97
	v_mul_f32_e32 v98, v128, v98
	v_mul_f32_e32 v99, v128, v99
	v_mul_f32_e32 v100, v129, v100
	v_mul_f32_e32 v101, v129, v101
	v_mul_f32_e32 v102, v129, v102
	v_mul_f32_e32 v103, v129, v103
	v_mul_f32_e32 v104, v130, v104
	v_mul_f32_e32 v105, v130, v105
	v_mul_f32_e32 v106, v130, v106
	v_mul_f32_e32 v107, v130, v107
	v_mul_f32_e32 v108, v131, v108
	v_mul_f32_e32 v109, v131, v109
	v_mul_f32_e32 v110, v131, v110
	v_mul_f32_e32 v111, v131, v111
	v_mul_f32_e32 v112, v132, v112
	v_mul_f32_e32 v113, v132, v113
	v_mul_f32_e32 v114, v132, v114
	v_mul_f32_e32 v115, v132, v115
	v_mul_f32_e32 v116, v133, v116
	v_mul_f32_e32 v117, v133, v117
	v_mul_f32_e32 v118, v133, v118
	v_mul_f32_e32 v119, v133, v119
	v_mul_f32_e32 v120, v134, v120
	v_mul_f32_e32 v121, v134, v121
	v_mul_f32_e32 v122, v134, v122
	v_mul_f32_e32 v123, v134, v123
	v_mul_f32_e32 v124, v135, v124
	v_mul_f32_e32 v125, v135, v125
	v_mul_f32_e32 v126, v135, v126
	v_mul_f32_e32 v127, v135, v127
.Lcw28_nog:
	v_cvt_pk_bf16_f32 v128, v96, v100
	v_cvt_pk_bf16_f32 v129, v104, v108
	v_cvt_pk_bf16_f32 v130, v112, v116
	v_cvt_pk_bf16_f32 v131, v120, v124
	global_store_dwordx4 v136, v[128:131], s[80:81]
	v_add_u32_e32 v136, s82, v136
	v_cvt_pk_bf16_f32 v132, v97, v101
	v_cvt_pk_bf16_f32 v133, v105, v109
	v_cvt_pk_bf16_f32 v134, v113, v117
	v_cvt_pk_bf16_f32 v135, v121, v125
	global_store_dwordx4 v136, v[132:135], s[80:81]
	v_add_u32_e32 v136, s82, v136
	v_cvt_pk_bf16_f32 v128, v98, v102
	v_cvt_pk_bf16_f32 v129, v106, v110
	v_cvt_pk_bf16_f32 v130, v114, v118
	v_cvt_pk_bf16_f32 v131, v122, v126
	global_store_dwordx4 v136, v[128:131], s[80:81]
	v_add_u32_e32 v136, s82, v136
	v_cvt_pk_bf16_f32 v132, v99, v103
	v_cvt_pk_bf16_f32 v133, v107, v111
	v_cvt_pk_bf16_f32 v134, v115, v119
	v_cvt_pk_bf16_f32 v135, v123, v127
	global_store_dwordx4 v136, v[132:135], s[80:81]
	s_waitcnt vmcnt(0)
	s_cmp_eq_u32 s75, 0
	s_cbranch_scc1 .Lcw29_nog
	v_mul_f32_e32 v8, v40, v8
	v_mul_f32_e32 v9, v40, v9
	v_mul_f32_e32 v10, v40, v10
	v_mul_f32_e32 v11, v40, v11
	v_mul_f32_e32 v12, v41, v12
	v_mul_f32_e32 v13, v41, v13
	v_mul_f32_e32 v14, v41, v14
	v_mul_f32_e32 v15, v41, v15
	v_mul_f32_e32 v16, v42, v16
	v_mul_f32_e32 v17, v42, v17
	v_mul_f32_e32 v18, v42, v18
	v_mul_f32_e32 v19, v42, v19
	v_mul_f32_e32 v20, v43, v20
	v_mul_f32_e32 v21, v43, v21
	v_mul_f32_e32 v22, v43, v22
	v_mul_f32_e32 v23, v43, v23
	v_mul_f32_e32 v24, v44, v24
	v_mul_f32_e32 v25, v44, v25
	v_mul_f32_e32 v26, v44, v26
	v_mul_f32_e32 v27, v44, v27
	v_mul_f32_e32 v28, v45, v28
	v_mul_f32_e32 v29, v45, v29
	v_mul_f32_e32 v30, v45, v30
	v_mul_f32_e32 v31, v45, v31
	v_mul_f32_e32 v32, v46, v32
	v_mul_f32_e32 v33, v46, v33
	v_mul_f32_e32 v34, v46, v34
	v_mul_f32_e32 v35, v46, v35
	v_mul_f32_e32 v36, v47, v36
	v_mul_f32_e32 v37, v47, v37
	v_mul_f32_e32 v38, v47, v38
	v_mul_f32_e32 v39, v47, v39

; __global__ void __launch_bounds__(NTHR) hybrid_encoder_fwd(Params P) {
;     ...
;                     attn_a_phase(lds, bid - 64, 192, 8, Qb, Kb, Vb, P.in[1], NUM, ML);
.Lcw_exit:
	v_readlane_b32 s0, v255, 16
	v_readlane_b32 s1, v255, 17
	v_readlane_b32 s3, v255, 18
	v_readlane_b32 s4, v255, 19
	v_readlane_b32 s5, v255, 20
	v_readlane_b32 s6, v255, 21
	v_readlane_b32 s7, v255, 22
	v_readlane_b32 s8, v255, 23
	v_readlane_b32 s9, v255, 24
	v_readlane_b32 s10, v255, 25
	v_readlane_b32 s11, v255, 26
	v_readlane_b32 s12, v255, 27
	v_readlane_b32 s13, v255, 28
	v_readlane_b32 s14, v255, 29
	v_readlane_b32 s15, v255, 30
	v_readlane_b32 s16, v255, 31
	v_readlane_b32 s17, v255, 32
	v_readlane_b32 s18, v255, 33
	v_readlane_b32 s19, v255, 34
	v_readlane_b32 s20, v255, 35
	v_readlane_b32 s21, v255, 36
	v_readlane_b32 s22, v255, 37
	v_readlane_b32 s23, v255, 38
	v_readlane_b32 s24, v255, 39
	v_readlane_b32 s25, v255, 40
	v_readlane_b32 s30, v255, 41
	v_readlane_b32 s33, v255, 42
	v_readlane_b32 s38, v255, 43
	v_readlane_b32 s39, v255, 44
	v_readlane_b32 s72, v255, 45
	v_readlane_b32 s73, v255, 46
	v_readlane_b32 s74, v255, 47
	v_readlane_b32 s75, v255, 48
	v_readlane_b32 s76, v255, 49
	v_readlane_b32 s77, v255, 50
	v_readlane_b32 s78, v255, 51
	v_readlane_b32 s79, v255, 52
	v_readlane_b32 s80, v255, 53
	v_readlane_b32 s81, v255, 54
	v_readlane_b32 s82, v255, 55
	v_readlane_b32 s83, v255, 56
	v_readlane_b32 s86, v255, 57
	v_readlane_b32 s87, v255, 58
	v_readlane_b32 s88, v255, 59
	v_readlane_b32 s89, v255, 60
	v_readlane_b32 vcc_lo, v255, 61
	v_readlane_b32 vcc_hi, v255, 62
	s_nop 3
	s_mov_b64 s[0:1], 0

; __global__ void __launch_bounds__(NTHR) hybrid_encoder_fwd(Params P) {
	.amdhsa_kernel _Z18hybrid_encoder_fwd6Params
		.amdhsa_group_segment_fixed_size 0
		.amdhsa_private_segment_fixed_size 0
		.amdhsa_kernarg_size 448
		.amdhsa_user_sgpr_count 2
		.amdhsa_user_sgpr_dispatch_ptr 0
		.amdhsa_user_sgpr_queue_ptr 0
		.amdhsa_user_sgpr_kernarg_segment_ptr 1
		.amdhsa_user_sgpr_dispatch_id 0
		.amdhsa_user_sgpr_kernarg_preload_length 0
		.amdhsa_user_sgpr_kernarg_preload_offset 0
		.amdhsa_user_sgpr_private_segment_size 0
		.amdhsa_uses_dynamic_stack 0
		.amdhsa_enable_private_segment 0
		.amdhsa_system_sgpr_workgroup_id_x 1
		.amdhsa_system_sgpr_workgroup_id_y 0
		.amdhsa_system_sgpr_workgroup_id_z 0
		.amdhsa_system_sgpr_workgroup_info 0
		.amdhsa_system_vgpr_workitem_id 2
		.amdhsa_next_free_vgpr 256
		.amdhsa_next_free_sgpr 100
		.amdhsa_accum_offset 256
		.amdhsa_reserve_vcc 1
		.amdhsa_float_round_mode_32 0
		.amdhsa_float_round_mode_16_64 0
		.amdhsa_float_denorm_mode_32 3
		.amdhsa_float_denorm_mode_16_64 3
		.amdhsa_dx10_clamp 1
		.amdhsa_ieee_mode 1
		.amdhsa_fp16_overflow 0
		.amdhsa_tg_split 0
		.amdhsa_exception_fp_ieee_invalid_op 0
		.amdhsa_exception_fp_denorm_src 0
		.amdhsa_exception_fp_ieee_div_zero 0
		.amdhsa_exception_fp_ieee_overflow 0
		.amdhsa_exception_fp_ieee_underflow 0
		.amdhsa_exception_fp_ieee_inexact 0
		.amdhsa_exception_int_div_zero 0
	.end_amdhsa_kernel

; __global__ void __launch_bounds__(NTHR) hybrid_encoder_fwd(Params P) {
amdhsa.kernels:
  - .agpr_count:     0
    .args:
      - .offset:         0
        .size:           192
        .value_kind:     by_value
      - .offset:         192
        .size:           4
        .value_kind:     hidden_block_count_x
      - .offset:         196
        .size:           4
        .value_kind:     hidden_block_count_y
      - .offset:         200
        .size:           4
        .value_kind:     hidden_block_count_z
      - .offset:         204
        .size:           2
        .value_kind:     hidden_group_size_x
      - .offset:         206
        .size:           2
        .value_kind:     hidden_group_size_y
      - .offset:         208
        .size:           2
        .value_kind:     hidden_group_size_z
      - .offset:         210
        .size:           2
        .value_kind:     hidden_remainder_x
      - .offset:         212
        .size:           2
        .value_kind:     hidden_remainder_y
      - .offset:         214
        .size:           2
        .value_kind:     hidden_remainder_z
      - .offset:         232
        .size:           8
        .value_kind:     hidden_global_offset_x
      - .offset:         240
        .size:           8
        .value_kind:     hidden_global_offset_y
      - .offset:         248
        .size:           8
        .value_kind:     hidden_global_offset_z
      - .offset:         256
        .size:           2
        .value_kind:     hidden_grid_dims
      - .offset:         280
        .size:           8
        .value_kind:     hidden_multigrid_sync_arg
      - .offset:         312
        .size:           4
        .value_kind:     hidden_dynamic_lds_size
    .group_segment_fixed_size: 0
    .kernarg_segment_align: 8
    .kernarg_segment_size: 448
    .language:       OpenCL C
    .language_version:
      - 2
      - 0
    .max_flat_workgroup_size: 512
    .name:           _Z18hybrid_encoder_fwd6Params
    .private_segment_fixed_size: 0
    .sgpr_count:     106
    .sgpr_spill_count: 167
    .symbol:         _Z18hybrid_encoder_fwd6Params.kd
    .uniform_work_group_size: 1
    .uses_dynamic_stack: false
    .vgpr_count:     256
    .vgpr_spill_count: 0
    .wavefront_size: 64
